# PE loop: deferred kpe unpack (one load round trip per row) + dead SGPR reloads removed; pc_rows: q/kv norm gains hoisted out of the row loop
# speedup vs baseline: 1.0117x; 1.0117x over previous
.LBB0_417:
	s_andn2_b64 vcc, exec, s[2:3]
	s_cbranch_vccnz .LBB0_419
	v_lshl_add_u64 v[22:23], s[18:19], 0, v[56:57]
	global_load_dwordx2 v[90:91], v[22:23], off

.LBB0_421:
	v_cndmask_b32_e64 v23, 0, 1, s[0:1]
	v_cmp_ne_u32_e64 s[38:39], 1, v23
	s_andn2_b64 vcc, exec, s[0:1]
	v_lshl_add_u64 v[68:69], s[18:19], 0, v[60:61]
	v_mov_b32_e32 v23, 0
	v_mov_b32_e32 v24, 0
	v_mov_b32_e32 v25, 0
	v_mov_b32_e32 v34, 0
	v_mov_b32_e32 v35, 0
	v_mov_b32_e32 v36, 0
	v_mov_b32_e32 v37, 0
	v_mov_b32_e32 v38, 0
	v_mov_b32_e32 v39, 0
	v_mov_b32_e32 v40, 0
	v_mov_b32_e32 v41, 0
	s_cbranch_vccnz .LBB0_423
	v_add_co_u32_e32 v22, vcc, 0xd490000, v68
	s_nop 0
	v_addc_co_u32_e32 v23, vcc, 0, v69, vcc
	v_add_co_u32_e32 v24, vcc, 0xe090000, v68
	v_addc_co_u32_e32 v25, vcc, 0, v69, vcc
	global_load_dwordx4 v[38:41], v[22:23], off
	global_load_dwordx4 v[34:37], v[24:25], off
	v_lshl_add_u64 v[22:23], s[18:19], 0, v[58:59]
	global_load_dwordx4 v[22:25], v[22:23], off
.LBB0_423:
	v_cndmask_b32_e64 v27, 0, 1, s[36:37]
	v_mov_b32_e32 v26, 0
	v_cmp_ne_u32_e64 s[0:1], 1, v27
	s_andn2_b64 vcc, exec, s[36:37]
	v_mov_b32_e32 v27, 0
	v_mov_b32_e32 v28, 0
	v_mov_b32_e32 v29, 0
	v_mov_b32_e32 v30, 0
	v_mov_b32_e32 v31, 0
	v_mov_b32_e32 v32, 0
	v_mov_b32_e32 v33, 0
	s_cbranch_vccnz .LBB0_425
	s_mov_b32 s7, s4
	s_lshl_b64 s[2:3], s[6:7], 1
	s_add_u32 s2, s18, s2
	v_add_co_u32_e32 v26, vcc, 0x15f90000, v68
	s_addc_u32 s3, s19, s3
	s_nop 0
	v_addc_co_u32_e32 v27, vcc, 0, v69, vcc
	v_lshl_add_u64 v[28:29], s[2:3], 0, v[0:1]
	v_add_co_u32_e32 v30, vcc, 0x1c01c000, v28
	s_nop 0
	v_addc_co_u32_e32 v31, vcc, 0, v29, vcc
	global_load_dwordx4 v[26:29], v[26:27], off
	s_nop 0
	global_load_dwordx4 v[30:33], v[30:31], off
.LBB0_425:
	s_waitcnt vmcnt(0)
	s_and_b64 vcc, exec, s[38:39]
	s_cbranch_vccnz .Lpe_kpe_done
	v_lshlrev_b32_e32 v46, 16, v90
	v_and_b32_e32 v47, 0xffff0000, v90
	v_lshlrev_b32_e32 v48, 16, v91
	v_and_b32_e32 v49, 0xffff0000, v91
.Lpe_kpe_done:
	v_mul_f32_e32 v84, v47, v47
	v_fmac_f32_e32 v84, v46, v46
	v_fmac_f32_e32 v84, v48, v48
	v_lshlrev_b32_e32 v82, 16, v42
	v_and_b32_e32 v83, 0xffff0000, v42
	v_fmac_f32_e32 v84, v49, v49
	v_lshlrev_b32_e32 v78, 16, v43
	v_and_b32_e32 v79, 0xffff0000, v43
	v_pk_mul_f32 v[42:43], v[82:83], v[82:83]
	v_pk_mul_f32 v[80:81], v[78:79], v[78:79]
	v_add_f32_e32 v42, v42, v84
	v_add_f32_e32 v42, v43, v42
	v_lshlrev_b32_e32 v76, 16, v44
	v_and_b32_e32 v77, 0xffff0000, v44
	v_add_f32_e32 v42, v80, v42
	v_lshlrev_b32_e32 v72, 16, v45
	v_and_b32_e32 v73, 0xffff0000, v45
	v_pk_mul_f32 v[44:45], v[76:77], v[76:77]
	v_add_f32_e32 v42, v81, v42
	v_add_f32_e32 v42, v44, v42
	v_pk_mul_f32 v[74:75], v[72:73], v[72:73]
	v_add_f32_e32 v42, v45, v42
	v_add_f32_e32 v42, v74, v42
	v_add_f32_e32 v42, v75, v42
	ds_bpermute_b32 v43, v55, v42
	s_and_b64 vcc, exec, s[38:39]
	s_waitcnt lgkmcnt(0)
	v_add_f32_e32 v42, v42, v43
	ds_bpermute_b32 v43, v70, v42
	s_waitcnt lgkmcnt(0)
	v_add_f32_e32 v42, v42, v43
	ds_bpermute_b32 v43, v71, v42
	s_waitcnt lgkmcnt(0)
	v_add_f32_e32 v42, v42, v43
	v_fmamk_f32 v42, v42, 0x3c2aaaab, v248
	v_rsq_f32_e32 v42, v42
	s_nop 0
	v_pk_mul_f32 v[74:75], v[8:9], v[42:43] op_sel_hi:[1,0]
	s_nop 0
	v_pk_mul_f32 v[74:75], v[74:75], v[78:79]
	v_pk_mul_f32 v[78:79], v[4:5], v[42:43] op_sel_hi:[1,0]
	v_pk_mul_f32 v[44:45], v[6:7], v[42:43] op_sel_hi:[1,0]
	v_pk_mul_f32 v[72:73], v[78:79], v[72:73]
	v_pk_mul_f32 v[78:79], v[10:11], v[42:43] op_sel_hi:[1,0]
	v_pk_mul_f32 v[80:81], v[2:3], v[42:43] op_sel_hi:[1,0]
	v_pk_mul_f32 v[46:47], v[46:47], v[78:79]
	v_pk_mul_f32 v[42:43], v[12:13], v[42:43] op_sel_hi:[1,0]
	v_pk_mul_f32 v[44:45], v[44:45], v[82:83]
	v_pk_mul_f32 v[42:43], v[48:49], v[42:43]
	v_pk_mul_f32 v[48:49], v[50:51], v[46:47] op_sel:[1,1] op_sel_hi:[0,1]
	v_pk_fma_f32 v[78:79], v[50:51], v[46:47], v[48:49] op_sel_hi:[1,0,1] neg_lo:[0,0,1] neg_hi:[0,0,1]
	v_pk_fma_f32 v[48:49], v[50:51], v[46:47], v[48:49] op_sel_hi:[1,0,1]
	v_pk_mul_f32 v[50:51], v[52:53], v[42:43] op_sel:[1,1] op_sel_hi:[0,1]
	v_pk_mul_f32 v[76:77], v[80:81], v[76:77]
	v_pk_fma_f32 v[80:81], v[52:53], v[42:43], v[50:51] op_sel_hi:[1,0,1] neg_lo:[0,0,1] neg_hi:[0,0,1]
	v_pk_fma_f32 v[50:51], v[52:53], v[42:43], v[50:51] op_sel_hi:[1,0,1]
	v_cndmask_b32_e64 v49, v47, v49, s[36:37]
	v_cndmask_b32_e64 v48, v43, v51, s[36:37]
	v_cndmask_b32_e64 v50, v42, v80, s[36:37]
	v_cndmask_b32_e64 v51, v46, v78, s[36:37]
	v_cvt_pk_bf16_f32 v42, v44, v45
	v_cvt_pk_bf16_f32 v43, v74, v75
	v_cvt_pk_bf16_f32 v44, v76, v77
	v_cvt_pk_bf16_f32 v45, v72, v73
	v_lshl_add_u64 v[46:47], s[18:19], 0, v[64:65]
	global_store_dwordx4 v[46:47], v[42:45], off
	s_nop 1
	v_cvt_pk_bf16_f32 v42, v51, v49
	v_cvt_pk_bf16_f32 v43, v50, v48
	v_lshl_add_u64 v[44:45], s[18:19], 0, v[62:63]
	global_store_dwordx2 v[44:45], v[42:43], off
	s_cbranch_vccnz .LBB0_427
	v_lshlrev_b32_e32 v42, 16, v38
	v_and_b32_e32 v43, 0xffff0000, v38
	v_lshlrev_b32_e32 v44, 16, v34
	v_and_b32_e32 v45, 0xffff0000, v34
	v_lshlrev_b32_e32 v38, 16, v39
	v_and_b32_e32 v39, 0xffff0000, v39
	v_lshlrev_b32_e32 v34, 16, v35
	v_and_b32_e32 v35, 0xffff0000, v35
	v_pk_add_f32 v[34:35], v[34:35], v[38:39]
	v_lshlrev_b32_e32 v38, 16, v23
	v_and_b32_e32 v39, 0xffff0000, v23
	v_pk_fma_f32 v[34:35], v[16:17], v[38:39], v[34:35]
	v_pk_add_f32 v[42:43], v[44:45], v[42:43]
	v_mul_f32_e32 v23, 0x3d372713, v34
	v_mul_f32_e32 v23, v34, v23
	v_fma_f32 v23, v34, v23, v34
	v_mul_f32_e32 v23, 0x3f4c422a, v23
	v_add_f32_e32 v23, v23, v23
	v_mul_f32_e32 v23, 0xbfb8aa3b, v23
	v_exp_f32_e32 v23, v23
	v_lshlrev_b32_e32 v44, 16, v22
	v_and_b32_e32 v45, 0xffff0000, v22
	v_pk_fma_f32 v[42:43], v[14:15], v[44:45], v[42:43]
	v_add_f32_e32 v23, 1.0, v23
	v_rcp_f32_e32 v38, v23
	v_mul_f32_e32 v23, 0x3d372713, v35
	v_mul_f32_e32 v23, v35, v23
	v_fma_f32 v23, v35, v23, v35
	v_mul_f32_e32 v23, 0x3f4c422a, v23
	v_add_f32_e32 v23, v23, v23
	v_mul_f32_e32 v23, 0xbfb8aa3b, v23
	v_exp_f32_e32 v23, v23
	v_mul_f32_e32 v22, 0x3d372713, v42
	v_mul_f32_e32 v22, v42, v22
	v_fma_f32 v22, v42, v22, v42
	v_add_f32_e32 v23, 1.0, v23
	v_rcp_f32_e32 v39, v23
	v_mul_f32_e32 v22, 0x3f4c422a, v22
	v_add_f32_e32 v22, v22, v22
	v_mul_f32_e32 v22, 0xbfb8aa3b, v22
	v_pk_mul_f32 v[34:35], v[34:35], v[38:39]
	v_lshlrev_b32_e32 v38, 16, v36
	v_cvt_pk_bf16_f32 v23, v34, v35
	v_lshlrev_b32_e32 v34, 16, v40
	v_and_b32_e32 v35, 0xffff0000, v40
	v_and_b32_e32 v39, 0xffff0000, v36
	v_pk_add_f32 v[34:35], v[38:39], v[34:35]
	v_lshlrev_b32_e32 v38, 16, v24
	v_and_b32_e32 v39, 0xffff0000, v24
	v_pk_fma_f32 v[34:35], v[18:19], v[38:39], v[34:35]
	v_lshlrev_b32_e32 v36, 16, v37
	v_mul_f32_e32 v24, 0x3d372713, v34
	v_mul_f32_e32 v24, v34, v24
	v_fma_f32 v24, v34, v24, v34
	v_mul_f32_e32 v24, 0x3f4c422a, v24
	v_add_f32_e32 v24, v24, v24
	v_mul_f32_e32 v24, 0xbfb8aa3b, v24
	v_exp_f32_e32 v24, v24
	v_and_b32_e32 v37, 0xffff0000, v37
	v_exp_f32_e32 v22, v22
	v_add_f32_e32 v24, 1.0, v24
	v_rcp_f32_e32 v38, v24
	v_mul_f32_e32 v24, 0x3d372713, v35
	v_mul_f32_e32 v24, v35, v24
	v_fma_f32 v24, v35, v24, v35
	v_mul_f32_e32 v24, 0x3f4c422a, v24
	v_add_f32_e32 v24, v24, v24
	v_mul_f32_e32 v24, 0xbfb8aa3b, v24
	v_exp_f32_e32 v24, v24
	v_add_f32_e32 v22, 1.0, v22
	v_rcp_f32_e32 v44, v22
	v_mul_f32_e32 v22, 0x3d372713, v43
	v_add_f32_e32 v24, 1.0, v24
	v_rcp_f32_e32 v39, v24
	v_mul_f32_e32 v22, v43, v22
	v_fma_f32 v22, v43, v22, v43
	v_mul_f32_e32 v22, 0x3f4c422a, v22
	v_pk_mul_f32 v[34:35], v[34:35], v[38:39]
	v_add_f32_e32 v22, v22, v22
	v_cvt_pk_bf16_f32 v24, v34, v35
	v_lshlrev_b32_e32 v34, 16, v41
	v_and_b32_e32 v35, 0xffff0000, v41
	v_pk_add_f32 v[34:35], v[36:37], v[34:35]
	v_lshlrev_b32_e32 v36, 16, v25
	v_and_b32_e32 v37, 0xffff0000, v25
	v_pk_fma_f32 v[34:35], v[20:21], v[36:37], v[34:35]
	v_mul_f32_e32 v22, 0xbfb8aa3b, v22
	v_mul_f32_e32 v25, 0x3d372713, v34
	v_mul_f32_e32 v25, v34, v25
	v_fma_f32 v25, v34, v25, v34
	v_mul_f32_e32 v25, 0x3f4c422a, v25
	v_add_f32_e32 v25, v25, v25
	v_mul_f32_e32 v25, 0xbfb8aa3b, v25
	v_exp_f32_e32 v25, v25
	v_exp_f32_e32 v22, v22
	v_add_f32_e32 v25, 1.0, v25
	v_rcp_f32_e32 v36, v25
	v_mul_f32_e32 v25, 0x3d372713, v35
	v_mul_f32_e32 v25, v35, v25
	v_fma_f32 v25, v35, v25, v35
	v_mul_f32_e32 v25, 0x3f4c422a, v25
	v_add_f32_e32 v25, v25, v25
	v_mul_f32_e32 v25, 0xbfb8aa3b, v25
	v_exp_f32_e32 v25, v25
	v_add_f32_e32 v22, 1.0, v22
	v_rcp_f32_e32 v45, v22
	v_add_f32_e32 v25, 1.0, v25
	v_rcp_f32_e32 v37, v25
	v_pk_mul_f32 v[42:43], v[42:43], v[44:45]
	v_pk_mul_f32 v[34:35], v[34:35], v[36:37]
	s_nop 0
	v_cvt_pk_bf16_f32 v25, v34, v35
	v_add_co_u32_e32 v34, vcc, 0xec90000, v68
	v_cvt_pk_bf16_f32 v22, v42, v43
	s_nop 0
	v_addc_co_u32_e32 v35, vcc, 0, v69, vcc
	global_store_dwordx4 v[34:35], v[22:25], off

.LBB0_524:
	s_mul_i32 s0, s30, 0x600
	s_mov_b32 s38, s21
	s_ashr_i32 s1, s0, 31
	v_readlane_b32 s8, v255, 32
	s_lshl_b64 s[0:1], s[0:1], 2
	v_readlane_b32 s14, v255, 38
	v_readlane_b32 s15, v255, 39
	s_add_u32 s0, s14, s0
	s_addc_u32 s1, s15, s1
	s_waitcnt vmcnt(0)
	v_lshlrev_b32_e32 v14, 5, v204
	v_mov_b32_e32 v15, v1
	v_lshl_add_u64 v[18:19], s[0:1], 0, v[14:15]
	s_mov_b64 s[2:3], 0x1000
	global_load_dwordx4 v[2:5], v14, s[0:1] offset:16
	global_load_dwordx4 v[6:9], v14, s[0:1]
	global_load_dwordx4 v[10:13], v14, s[0:1] offset:2064
	s_nop 0
	global_load_dwordx4 v[14:17], v14, s[0:1] offset:2048
	s_movk_i32 s0, 0x1000
	v_lshl_add_u64 v[22:23], v[18:19], 0, s[2:3]
	v_add_co_u32_e32 v18, vcc, s0, v18
	s_lshl_b32 s0, s30, 8
	s_nop 0
	v_addc_co_u32_e32 v19, vcc, 0, v19, vcc
	global_load_dwordx4 v[18:21], v[18:19], off
	s_nop 0
	global_load_dwordx4 v[22:25], v[22:23], off offset:16
	s_ashr_i32 s1, s0, 31
	v_readlane_b32 s80, v255, 0
	s_lshl_b64 s[0:1], s[0:1], 2
	v_readlane_b32 s90, v255, 10
	v_readlane_b32 s91, v255, 11
	s_add_u32 s2, s90, s0
	s_mul_i32 s0, s30, 0x180
	v_lshlrev_b32_e32 v0, 3, v204
	s_addc_u32 s3, s91, s1
	s_ashr_i32 s1, s0, 31
	v_readlane_b32 s88, v255, 8
	s_lshl_b64 s[0:1], s[0:1], 2
	v_lshl_add_u64 v[56:57], s[2:3], 0, v[0:1]
	v_readlane_b32 s2, v251, 29
	v_readlane_b32 s9, v255, 33
	v_readlane_b32 s89, v255, 9
	s_add_u32 s8, s88, s0
	v_readlane_b32 s3, v251, 30
	s_addc_u32 s9, s89, s1
	s_ashr_i32 s31, s30, 31
	v_lshl_add_u64 v[60:61], s[2:3], 0, v[0:1]
	v_readlane_b32 s2, v253, 43
	v_lshl_add_u64 v[54:55], s[8:9], 0, v[0:1]
	v_readlane_b32 s8, v251, 27
	v_readlane_b32 s3, v253, 44
	s_ashr_i32 s67, s66, 31
	s_lshl_b64 s[6:7], s[30:31], 8
	v_readlane_b32 s9, v251, 28
	v_lshl_add_u64 v[62:63], s[2:3], 0, v[0:1]
	s_lshl_b64 s[2:3], s[66:67], 10
	v_lshl_add_u64 v[58:59], s[8:9], 0, v[0:1]
	global_load_dwordx2 v[160:161], v[54:55], off
	global_load_dwordx2 v[162:163], v[54:55], off offset:512
	global_load_dwordx2 v[164:165], v[54:55], off offset:1024
	global_load_dwordx2 v[166:167], v[56:57], off
	global_load_dwordx2 v[168:169], v[56:57], off offset:512
	v_or_b32_e32 v0, 0x200, v0
	s_add_u32 s2, s2, 0x17790000
	v_lshl_add_u64 v[64:65], s[8:9], 0, v[0:1]
	s_addc_u32 s3, s3, 0
	v_lshlrev_b32_e32 v0, 4, v204
	v_lshlrev_b32_e32 v26, 2, v204
	v_or_b32_e32 v66, s2, v0
	v_mov_b32_e32 v67, s3
	s_lshl_b64 s[2:3], s[66:67], 9
	v_or_b32_e32 v68, s2, v26
	v_mov_b32_e32 v69, s3
	s_mul_hi_i32 s2, s66, 0x300
	s_mul_i32 s3, s66, 0x300
	v_mov_b32_e32 v27, 0x1a00
	v_readlane_b32 s18, v255, 42
	v_readlane_b32 s19, v255, 43
	v_or_b32_e32 v70, s3, v26
	v_mov_b32_e32 v71, s2
	v_mad_i64_i32 v[72:73], s[2:3], s66, v27, v[0:1]
	s_mul_hi_i32 s5, s66, 0x1a00
	s_mul_i32 s8, s66, 0x1a00
	s_lshl_b32 s2, s27, 8
	v_readlane_b32 s3, v254, 36
	v_readlane_b32 s18, v254, 34
	v_readlane_b32 s36, v254, 38
	v_cmp_gt_u32_e64 s[0:1], 16, v204
	v_or_b32_e32 v74, s8, v26
	v_mov_b32_e32 v75, s5
	s_add_i32 s5, s3, s2
	v_lshlrev_b32_e32 v0, 2, v26
	s_mov_b32 s8, s66
	v_readlane_b32 s19, v254, 35
	v_readlane_b32 s34, v254, 37
	v_readlane_b32 s37, v254, 39
	v_readlane_b32 s10, v255, 34
	v_readlane_b32 s11, v255, 35
	v_readlane_b32 s12, v255, 36
	v_readlane_b32 s13, v255, 37
	v_readlane_b32 s16, v255, 40
	v_readlane_b32 s17, v255, 41
	v_readlane_b32 s20, v255, 44
	v_readlane_b32 s21, v255, 45
	v_readlane_b32 s22, v255, 46
	v_readlane_b32 s23, v255, 47
	v_readlane_b32 s81, v255, 1
	v_readlane_b32 s82, v255, 2
	v_readlane_b32 s83, v255, 3
	v_readlane_b32 s84, v255, 4
	v_readlane_b32 s85, v255, 5
	v_readlane_b32 s86, v255, 6
	v_readlane_b32 s87, v255, 7
	v_readlane_b32 s92, v255, 12
	v_readlane_b32 s93, v255, 13
	v_readlane_b32 s94, v255, 14
	v_readlane_b32 s95, v255, 15
	s_branch .LBB0_526

.LBB0_534:
	s_waitcnt vmcnt(0)
	v_lshlrev_b32_e32 v86, 16, v80
	v_and_b32_e32 v87, 0xffff0000, v80
	v_and_b32_e32 v80, 64, v232
	v_lshlrev_b32_e32 v76, 16, v82
	v_and_b32_e32 v77, 0xffff0000, v82
	v_lshlrev_b32_e32 v82, 16, v81
	v_and_b32_e32 v83, 0xffff0000, v81
	v_add_u32_e32 v80, 64, v80
	v_xor_b32_e32 v81, 1, v232
	v_cmp_lt_i32_e32 vcc, v81, v80
	v_mov_b32_e32 v96, v77
	v_mov_b32_e32 v97, v87
	v_cndmask_b32_e32 v81, v232, v81, vcc
	v_lshlrev_b32_e32 v85, 2, v81
	v_xor_b32_e32 v81, 2, v232
	v_cmp_lt_i32_e32 vcc, v81, v80
	v_pk_mul_f32 v[90:91], v[82:83], v[82:83]
	v_mov_b32_e32 v94, v76
	v_cndmask_b32_e32 v81, v232, v81, vcc
	v_lshlrev_b32_e32 v98, 2, v81
	v_xor_b32_e32 v81, 4, v232
	v_cmp_lt_i32_e32 vcc, v81, v80
	v_mov_b32_e32 v95, v86
	v_pk_mul_f32 v[96:97], v[96:97], v[96:97]
	v_cndmask_b32_e32 v81, v232, v81, vcc
	v_lshlrev_b32_e32 v99, 2, v81
	v_xor_b32_e32 v81, 8, v232
	v_cmp_lt_i32_e32 vcc, v81, v80
	v_pk_fma_f32 v[94:95], v[94:95], v[94:95], v[96:97]
	v_add_f32_e32 v90, v90, v91
	v_cndmask_b32_e32 v81, v232, v81, vcc
	v_lshlrev_b32_e32 v100, 2, v81
	v_xor_b32_e32 v81, 16, v232
	v_cmp_lt_i32_e32 vcc, v81, v80
	v_add_f32_e32 v90, v94, v90
	v_add_f32_e32 v90, v90, v95
	v_cndmask_b32_e32 v81, v232, v81, vcc
	v_lshlrev_b32_e32 v101, 2, v81
	v_xor_b32_e32 v81, 32, v232
	v_cmp_lt_i32_e32 vcc, v81, v80
	ds_bpermute_b32 v91, v85, v90
	v_readlane_b32 s80, v249, 0
	v_cndmask_b32_e32 v80, v232, v81, vcc
	v_lshlrev_b32_e32 v102, 2, v80
	s_waitcnt lgkmcnt(0)
	v_add_f32_e32 v90, v90, v91
	ds_bpermute_b32 v91, v98, v90
	v_readlane_b32 s86, v249, 6
	v_readlane_b32 s87, v249, 7
	s_mov_b32 s2, 0xec90000
	v_readlane_b32 s81, v249, 1
	s_waitcnt lgkmcnt(0)
	v_add_f32_e32 v90, v90, v91
	ds_bpermute_b32 v91, v99, v90
	v_lshl_add_u64 v[88:89], s[86:87], 0, v[70:71]
	v_readlane_b32 s82, v249, 2
	v_readlane_b32 s83, v249, 3
	v_readlane_b32 s84, v249, 4
	s_waitcnt lgkmcnt(0)
	v_add_f32_e32 v90, v90, v91
	ds_bpermute_b32 v91, v100, v90
	v_readlane_b32 s85, v249, 5
	s_waitcnt lgkmcnt(0)
	v_add_f32_e32 v90, v90, v91
	ds_bpermute_b32 v91, v101, v90
	s_waitcnt lgkmcnt(0)
	v_add_f32_e32 v90, v90, v91
	ds_bpermute_b32 v91, v102, v90
	s_waitcnt lgkmcnt(0)
	v_add_f32_e32 v90, v90, v91
	v_fmamk_f32 v90, v90, 0x3b2aaaab, v248
	v_rsq_f32_e32 v90, v90
	s_nop 0
	v_pk_mul_f32 v[76:77], v[90:91], v[76:77] op_sel_hi:[0,1]
	s_nop 0
	v_pk_mul_f32 v[76:77], v[160:161], v[76:77]
	s_nop 0
	v_cvt_pk_bf16_f32 v80, v76, v77
	v_add_co_u32_e32 v76, vcc, s2, v88
	s_ashr_i32 s2, s8, 8
	s_nop 0
	v_addc_co_u32_e32 v77, vcc, 0, v89, vcc
	global_store_dword v[76:77], v80, off
	v_pk_mul_f32 v[80:81], v[90:91], v[82:83] op_sel_hi:[0,1]
	s_nop 0
	v_pk_mul_f32 v[80:81], v[162:163], v[80:81]
	s_ashr_i32 s3, s2, 31
	v_cvt_pk_bf16_f32 v80, v80, v81
	global_store_dword v[76:77], v80, off offset:256
	v_pk_mul_f32 v[80:81], v[90:91], v[86:87] op_sel_hi:[0,1]
	s_lshl_b64 s[2:3], s[2:3], 10
	s_add_u32 s14, s2, s6
	s_addc_u32 s15, s3, s7
	s_mov_b64 s[2:3], -1
	v_pk_mul_f32 v[80:81], v[80:81], v[164:165]
	s_nop 0
	v_cvt_pk_bf16_f32 v80, v80, v81
	global_store_dword v[76:77], v80, off offset:512
	v_and_b32_e32 v81, 0xffff0000, v79
	v_and_b32_e32 v77, 0xffff0000, v78
	v_lshlrev_b32_e32 v80, 16, v79
	v_lshlrev_b32_e32 v76, 16, v78
	v_mov_b32_e32 v82, v81
	v_mov_b32_e32 v83, v77
	v_mov_b32_e32 v78, v80
	v_mov_b32_e32 v79, v76
	v_pk_mul_f32 v[82:83], v[82:83], v[82:83]
	s_nop 0
	v_pk_fma_f32 v[78:79], v[78:79], v[78:79], v[82:83]
	s_nop 0
	v_add_f32_e32 v78, v78, v79
	ds_bpermute_b32 v79, v85, v78
	s_waitcnt lgkmcnt(0)
	v_add_f32_e32 v78, v78, v79
	ds_bpermute_b32 v79, v98, v78
	s_waitcnt lgkmcnt(0)
	v_add_f32_e32 v78, v78, v79
	ds_bpermute_b32 v79, v99, v78
	s_waitcnt lgkmcnt(0)
	v_add_f32_e32 v78, v78, v79
	ds_bpermute_b32 v79, v100, v78
	s_waitcnt lgkmcnt(0)
	v_add_f32_e32 v78, v78, v79
	ds_bpermute_b32 v79, v101, v78
	s_waitcnt lgkmcnt(0)
	v_add_f32_e32 v78, v78, v79
	ds_bpermute_b32 v79, v102, v78
	s_waitcnt lgkmcnt(0)
	v_add_f32_e32 v78, v78, v79
	v_fmamk_f32 v78, v78, 0x3b800000, v248
	v_rsq_f32_e32 v78, v78
	s_nop 0
	v_mov_b32_e32 v79, v78
	v_pk_mul_f32 v[80:81], v[78:79], v[80:81] op_sel_hi:[0,1]
	v_pk_mul_f32 v[76:77], v[78:79], v[76:77]
	v_pk_mul_f32 v[82:83], v[166:167], v[80:81]
	v_lshl_add_u64 v[80:81], s[86:87], 0, v[68:69]
	v_add_co_u32_e32 v86, vcc, 0xf590000, v80
	v_cvt_pk_bf16_f32 v85, v82, v83
	s_nop 0
	v_addc_co_u32_e32 v87, vcc, 0, v81, vcc
	s_and_b64 vcc, exec, s[12:13]
	global_store_dword v[86:87], v85, off
	s_cbranch_vccz .LBB0_541
	v_pk_mul_f32 v[78:79], v[76:77], v[168:169]
	s_nop 0
	v_cvt_pk_bf16_f32 v85, v78, v79
	v_add_co_u32_e32 v78, vcc, 0xf590000, v80
	s_nop 1
	v_addc_co_u32_e32 v79, vcc, 0, v81, vcc
	global_store_dword v[78:79], v85, off offset:256
	s_or_b32 s14, s14, s9
	s_cbranch_execz .LBB0_542

.LBB0_542:
	s_lshl_b64 s[2:3], s[14:15], 10
	v_lshl_add_u64 v[78:79], v[58:59], 0, s[2:3]
	global_store_dwordx2 v[78:79], v[82:83], off
	v_add_co_u32_e32 v80, vcc, 0xf590000, v80
	v_lshl_add_u64 v[82:83], v[64:65], 0, s[2:3]
	s_nop 0
	v_addc_co_u32_e32 v81, vcc, 0, v81, vcc
	v_pk_mul_f32 v[76:77], v[76:77], v[168:169]
	s_nop 0
	v_cvt_pk_bf16_f32 v78, v76, v77
	global_store_dword v[80:81], v78, off offset:256
	global_store_dwordx2 v[82:83], v[76:77], off
	s_and_saveexec_b64 s[2:3], s[10:11]
	s_cbranch_execnz .LBB0_537
	s_branch .LBB0_538
